# v24 + write-through (sc1) on the scan's per-chunk output stores (HY)
# baseline (speedup 1.0000x reference)
.LBB0_601:
	s_add_i32 s82, s22, -1
	s_add_i32 s83, s23, 1
	s_and_b64 s[26:27], s[14:15], exec
	s_cselect_b32 s26, s82, s83
	s_lshl_b32 s82, s26, 7
	v_add_u32_e32 v137, s52, v138
	v_mul_lo_u32 v68, v138, s88
	s_add_i32 s26, 0, 0x20000
	v_mul_lo_u32 v64, v137, s88
	v_lshl_add_u32 v65, v137, 2, 0
	v_lshlrev_b32_e32 v142, 4, v133
	v_add_u32_e32 v136, s26, v68
	v_mov_b32_e32 v0, s10
	v_add_u32_e32 v65, 0x26000, v65
	v_add_u32_e32 v143, 0, v64
	v_add_u32_e32 v80, v136, v142
	s_waitcnt lgkmcnt(0)
	s_barrier
	v_add_u32_e32 v144, v143, v142
	ds_read_b32 v0, v0
	ds_read_b32 v132, v65
	ds_read_b128 v[64:67], v144
	ds_read_b128 v[68:71], v80
	ds_read_b128 v[72:75], v80 offset:4608
	ds_read_b128 v[76:79], v80 offset:9216
	ds_read_b128 v[80:83], v80 offset:13824
	v_add_u32_e32 v84, s91, v138
	v_add_u32_e32 v173, s92, v138
	s_add_i32 s82, s82, s17
	v_mul_lo_u32 v145, v84, s88
	v_mul_lo_u32 v182, v173, s88
	v_add_u32_e32 v141, 64, v142
	v_add_u32_e32 v139, v136, v141
	ds_read_b128 v[84:87], v144 offset:64
	ds_read_b128 v[88:91], v139
	ds_read_b128 v[92:95], v139 offset:4608
	ds_read_b128 v[96:99], v139 offset:9216
	ds_read_b128 v[174:177], v139 offset:13824
	s_waitcnt lgkmcnt(8)
	v_mfma_f32_16x16x32_bf16 v[68:71], v[68:71], v[64:67], 0
	s_waitcnt lgkmcnt(7)
	v_mfma_f32_16x16x32_bf16 v[72:75], v[72:75], v[64:67], 0
	s_waitcnt lgkmcnt(6)
	v_mfma_f32_16x16x32_bf16 v[76:79], v[76:79], v[64:67], 0
	s_waitcnt lgkmcnt(5)
	v_mfma_f32_16x16x32_bf16 v[64:67], v[80:83], v[64:67], 0
	v_add_u32_e32 v140, 0x80, v142
	v_add_u32_e32 v139, v136, v140
	ds_read_b128 v[80:83], v144 offset:128
	ds_read_b128 v[178:181], v139
	ds_read_b128 v[190:193], v139 offset:4608
	ds_read_b128 v[194:197], v139 offset:9216
	ds_read_b128 v[198:201], v139 offset:13824
	s_waitcnt lgkmcnt(8)
	v_mfma_f32_16x16x32_bf16 v[68:71], v[88:91], v[84:87], v[68:71]
	s_waitcnt lgkmcnt(7)
	v_mfma_f32_16x16x32_bf16 v[72:75], v[92:95], v[84:87], v[72:75]
	s_waitcnt lgkmcnt(6)
	v_mfma_f32_16x16x32_bf16 v[76:79], v[96:99], v[84:87], v[76:79]
	s_waitcnt lgkmcnt(5)
	v_mfma_f32_16x16x32_bf16 v[64:67], v[174:177], v[84:87], v[64:67]
	v_add_u32_e32 v139, 0xc0, v142
	v_add_u32_e32 v174, v136, v139
	ds_read_b128 v[84:87], v144 offset:192
	ds_read_b128 v[88:91], v174
	ds_read_b128 v[92:95], v174 offset:4608
	ds_read_b128 v[96:99], v174 offset:9216
	ds_read_b128 v[174:177], v174 offset:13824
	s_waitcnt lgkmcnt(8)
	v_mfma_f32_16x16x32_bf16 v[68:71], v[178:181], v[80:83], v[68:71]
	s_waitcnt lgkmcnt(7)
	v_mfma_f32_16x16x32_bf16 v[72:75], v[190:193], v[80:83], v[72:75]
	s_waitcnt lgkmcnt(6)
	v_mfma_f32_16x16x32_bf16 v[76:79], v[194:197], v[80:83], v[76:79]
	s_waitcnt lgkmcnt(5)
	v_mfma_f32_16x16x32_bf16 v[64:67], v[198:201], v[80:83], v[64:67]
	v_add3_u32 v144, 0, v145, v142
	v_add3_u32 v145, 0, v182, v142
	ds_read_b128 v[80:83], v144 offset:36864
	ds_read_b128 v[178:181], v144 offset:41472
	ds_read_b128 v[190:193], v145
	ds_read_b128 v[194:197], v145 offset:4608
	ds_read_b128 v[198:201], v145 offset:9216
	ds_read_b128 v[202:205], v145 offset:13824
	s_waitcnt lgkmcnt(9)
	v_mfma_f32_16x16x32_bf16 v[68:71], v[88:91], v[84:87], v[68:71]
	s_waitcnt lgkmcnt(8)
	v_mfma_f32_16x16x32_bf16 v[88:91], v[92:95], v[84:87], v[72:75]
	s_waitcnt lgkmcnt(7)
	v_mfma_f32_16x16x32_bf16 v[92:95], v[96:99], v[84:87], v[76:79]
	s_waitcnt lgkmcnt(6)
	v_mfma_f32_16x16x32_bf16 v[64:67], v[174:177], v[84:87], v[64:67]
	s_nop 1
	v_mul_f32_e64 v74, v132, v70
	v_mul_f32_e64 v75, v132, v71
	v_pk_mul_f32 v[72:73], v[132:133], v[68:69] op_sel_hi:[0,1]
	v_pk_mul_f32 v[78:79], v[132:133], v[90:91] op_sel_hi:[0,1]
	v_pk_mul_f32 v[76:77], v[132:133], v[88:89] op_sel_hi:[0,1]
	v_pk_mul_f32 v[70:71], v[132:133], v[94:95] op_sel_hi:[0,1]
	v_pk_mul_f32 v[68:69], v[132:133], v[92:93] op_sel_hi:[0,1]
	ds_read_b128 v[84:87], v144 offset:36928
	ds_read_b128 v[88:91], v144 offset:41536
	ds_read_b128 v[92:95], v145 offset:64
	ds_read_b128 v[96:99], v145 offset:4672
	ds_read_b128 v[174:177], v145 offset:9280
	ds_read_b128 v[206:209], v145 offset:13888
	v_pk_mul_f32 v[66:67], v[132:133], v[66:67] op_sel_hi:[0,1]
	v_pk_mul_f32 v[64:65], v[132:133], v[64:65] op_sel_hi:[0,1]
	s_waitcnt lgkmcnt(9)
	v_mfma_f32_16x16x32_bf16 v[210:213], v[80:83], v[190:193], 0
	s_waitcnt lgkmcnt(8)
	v_mfma_f32_16x16x32_bf16 v[214:217], v[80:83], v[194:197], 0
	s_waitcnt lgkmcnt(7)
	v_mfma_f32_16x16x32_bf16 v[218:221], v[80:83], v[198:201], 0
	s_waitcnt lgkmcnt(6)
	v_mfma_f32_16x16x32_bf16 v[80:83], v[80:83], v[202:205], 0
	v_mfma_f32_16x16x32_bf16 v[190:193], v[178:181], v[190:193], 0
	v_mfma_f32_16x16x32_bf16 v[194:197], v[178:181], v[194:197], 0
	v_mfma_f32_16x16x32_bf16 v[198:201], v[178:181], v[198:201], 0
	v_mfma_f32_16x16x32_bf16 v[178:181], v[178:181], v[202:205], 0
	ds_read_b128 v[202:205], v144 offset:36992
	ds_read_b128 v[222:225], v144 offset:41600
	ds_read_b128 v[226:229], v145 offset:128
	ds_read_b128 v[230:233], v145 offset:4736
	ds_read_b128 v[234:237], v145 offset:9344
	ds_read_b128 v[238:241], v145 offset:13952
	s_waitcnt lgkmcnt(9)
	v_mfma_f32_16x16x32_bf16 v[210:213], v[84:87], v[92:95], v[210:213]
	s_waitcnt lgkmcnt(8)
	v_mfma_f32_16x16x32_bf16 v[214:217], v[84:87], v[96:99], v[214:217]
	s_waitcnt lgkmcnt(7)
	v_mfma_f32_16x16x32_bf16 v[218:221], v[84:87], v[174:177], v[218:221]
	s_waitcnt lgkmcnt(6)
	v_mfma_f32_16x16x32_bf16 v[80:83], v[84:87], v[206:209], v[80:83]
	v_mfma_f32_16x16x32_bf16 v[84:87], v[88:91], v[92:95], v[190:193]
	v_mfma_f32_16x16x32_bf16 v[92:95], v[88:91], v[96:99], v[194:197]
	v_mfma_f32_16x16x32_bf16 v[96:99], v[88:91], v[174:177], v[198:201]
	v_mfma_f32_16x16x32_bf16 v[88:91], v[88:91], v[206:209], v[178:181]
	ds_read_b128 v[174:177], v144 offset:37056
	s_nop 1
	ds_read_b128 v[178:181], v144 offset:41664
	ds_read_b128 v[190:193], v145 offset:192
	ds_read_b128 v[194:197], v145 offset:4800
	ds_read_b128 v[198:201], v145 offset:9408
	ds_read_b128 v[206:209], v145 offset:14016
	s_waitcnt lgkmcnt(9)
	v_mfma_f32_16x16x32_bf16 v[210:213], v[202:205], v[226:229], v[210:213]
	s_waitcnt lgkmcnt(8)
	v_mfma_f32_16x16x32_bf16 v[214:217], v[202:205], v[230:233], v[214:217]
	s_waitcnt lgkmcnt(7)
	v_mfma_f32_16x16x32_bf16 v[218:221], v[202:205], v[234:237], v[218:221]
	s_waitcnt lgkmcnt(6)
	v_mfma_f32_16x16x32_bf16 v[202:205], v[202:205], v[238:241], v[80:83]
	v_mfma_f32_16x16x32_bf16 v[226:229], v[222:225], v[226:229], v[84:87]
	v_mfma_f32_16x16x32_bf16 v[92:95], v[222:225], v[230:233], v[92:95]
	v_mfma_f32_16x16x32_bf16 v[230:233], v[222:225], v[234:237], v[96:99]
	v_mfma_f32_16x16x32_bf16 v[88:91], v[222:225], v[238:241], v[88:91]
	v_lshlrev_b32_e32 v132, 2, v133
	v_add_u32_e32 v183, s91, v132
	s_add_i32 s26, 0, 0x25c00
	v_lshlrev_b32_e32 v80, 2, v183
	s_add_i32 s27, 0, 0x25e00
	v_add_u32_e32 v81, s26, v80
	v_add_u32_e32 v80, s27, v80
	v_add_u32_e32 v238, s93, v132
	ds_read_b128 v[222:225], v81
	ds_read_b128 v[234:237], v80
	v_lshlrev_b32_e32 v80, 2, v238
	v_add_u32_e32 v81, s26, v80
	s_add_i32 s26, 0, 0x25a00
	v_lshl_add_u32 v96, v138, 2, s26
	v_add_u32_e32 v80, s27, v80
	v_add_u32_e32 v97, s94, v96
	ds_read_b128 v[84:87], v81
	ds_read_b128 v[80:83], v80
	v_add_u32_e32 v98, s95, v96
	v_add_u32_e32 v99, s96, v96
	v_add_u32_e32 v96, s97, v96
	ds_read_b32 v239, v97
	ds_read_b32 v240, v98
	ds_read_b32 v241, v99
	ds_read_b32 v242, v96
	s_waitcnt lgkmcnt(11)
	v_mfma_f32_16x16x32_bf16 v[210:213], v[174:177], v[190:193], v[210:213]
	s_waitcnt lgkmcnt(10)
	v_mfma_f32_16x16x32_bf16 v[214:217], v[174:177], v[194:197], v[214:217]
	s_waitcnt lgkmcnt(9)
	v_mfma_f32_16x16x32_bf16 v[218:221], v[174:177], v[198:201], v[218:221]
	s_waitcnt lgkmcnt(8)
	v_mfma_f32_16x16x32_bf16 v[174:177], v[174:177], v[206:209], v[202:205]
	v_mfma_f32_16x16x32_bf16 v[190:193], v[178:181], v[190:193], v[226:229]
	v_mfma_f32_16x16x32_bf16 v[96:99], v[178:181], v[194:197], v[92:95]
	v_mfma_f32_16x16x32_bf16 v[92:95], v[178:181], v[198:201], v[230:233]
	v_mfma_f32_16x16x32_bf16 v[88:91], v[178:181], v[206:209], v[88:91]
	s_waitcnt lgkmcnt(3)
	v_add_f32_e32 v144, v222, v239
	v_mul_f32_e32 v144, 0x3fb8aa3b, v144
	v_exp_f32_e32 v144, v144
	v_add_f32_e32 v145, v223, v239
	v_mul_f32_e32 v145, 0x3fb8aa3b, v145
	v_exp_f32_e32 v145, v145
	v_mul_f32_e32 v144, v234, v144
	v_cmp_le_i32_e32 vcc, v183, v173
	v_or_b32_e32 v181, 3, v183
	v_or_b32_e32 v194, 2, v183
	v_cndmask_b32_e32 v144, 0, v144, vcc
	v_mul_f32_e32 v178, v144, v210
	v_mul_f32_e32 v144, v235, v145
	v_cmp_lt_i32_e32 vcc, v183, v173
	v_add_f32_e32 v145, v225, v239
	v_mul_f32_e32 v145, 0x3fb8aa3b, v145
	v_cndmask_b32_e32 v179, 0, v144, vcc
	v_add_f32_e32 v144, v224, v239
	v_mul_f32_e32 v144, 0x3fb8aa3b, v144
	v_exp_f32_e32 v144, v144
	v_exp_f32_e32 v145, v145
	v_cmp_le_i32_e32 vcc, v181, v173
	s_add_i32 s83, 0, 0x12000
	v_mul_f32_e32 v179, v179, v211
	v_pk_mul_f32 v[144:145], v[236:237], v[144:145]
	v_lshl_add_u32 v180, v183, 1, s83
	v_cndmask_b32_e32 v145, 0, v145, vcc
	v_cmp_le_i32_e32 vcc, v194, v173
	v_cvt_pk_bf16_f32 v178, v178, v179
	v_add_u32_e32 v195, s3, v138
	v_cndmask_b32_e32 v144, 0, v144, vcc
	v_pk_mul_f32 v[144:145], v[144:145], v[212:213]
	v_cmp_le_i32_e32 vcc, v183, v195
	v_cvt_pk_bf16_f32 v179, v144, v145
	s_waitcnt lgkmcnt(2)
	v_add_f32_e32 v144, v222, v240
	v_mul_f32_e32 v144, 0x3fb8aa3b, v144
	v_add_u32_e32 v145, v180, v182
	v_exp_f32_e32 v144, v144
	ds_write_b64 v145, v[178:179]
	v_add_f32_e32 v145, v223, v240
	v_mul_f32_e32 v145, 0x3fb8aa3b, v145
	v_exp_f32_e32 v145, v145
	v_mul_f32_e32 v144, v234, v144
	v_cndmask_b32_e32 v144, 0, v144, vcc
	v_mul_f32_e32 v178, v144, v214
	v_mul_f32_e32 v179, v235, v145
	v_add_f32_e32 v144, v224, v240
	v_add_f32_e32 v145, v225, v240
	v_mul_f32_e32 v144, 0x3fb8aa3b, v144
	v_mul_f32_e32 v145, 0x3fb8aa3b, v145
	v_exp_f32_e32 v144, v144
	v_exp_f32_e32 v145, v145
	v_cmp_lt_i32_e32 vcc, v183, v195
	v_mul_lo_u32 v196, v195, s88
	v_add_u32_e32 v197, s18, v138
	v_cndmask_b32_e32 v179, 0, v179, vcc
	v_pk_mul_f32 v[144:145], v[236:237], v[144:145]
	v_cmp_le_i32_e32 vcc, v181, v195
	v_mul_f32_e32 v179, v179, v215
	v_cvt_pk_bf16_f32 v178, v178, v179
	v_cndmask_b32_e32 v145, 0, v145, vcc
	v_cmp_le_i32_e32 vcc, v194, v195
	v_mul_lo_u32 v198, v197, s88
	s_nop 0
	v_cndmask_b32_e32 v144, 0, v144, vcc
	v_pk_mul_f32 v[144:145], v[144:145], v[216:217]
	v_cmp_le_i32_e32 vcc, v183, v197
	v_cvt_pk_bf16_f32 v179, v144, v145
	s_waitcnt lgkmcnt(2)
	v_add_f32_e32 v144, v222, v241
	v_mul_f32_e32 v144, 0x3fb8aa3b, v144
	v_add_u32_e32 v145, v180, v196
	v_exp_f32_e32 v144, v144
	ds_write_b64 v145, v[178:179]
	v_add_f32_e32 v145, v223, v241
	v_mul_f32_e32 v145, 0x3fb8aa3b, v145
	v_exp_f32_e32 v145, v145
	v_mul_f32_e32 v144, v234, v144
	v_cndmask_b32_e32 v144, 0, v144, vcc
	v_mul_f32_e32 v178, v144, v218
	v_mul_f32_e32 v179, v235, v145
	v_add_f32_e32 v144, v224, v241
	v_add_f32_e32 v145, v225, v241
	v_mul_f32_e32 v144, 0x3fb8aa3b, v144
	v_mul_f32_e32 v145, 0x3fb8aa3b, v145
	v_exp_f32_e32 v144, v144
	v_exp_f32_e32 v145, v145
	v_cmp_lt_i32_e32 vcc, v183, v197
	v_pk_mul_f32 v[144:145], v[236:237], v[144:145]
	s_nop 0
	v_cndmask_b32_e32 v179, 0, v179, vcc
	v_cmp_le_i32_e32 vcc, v181, v197
	v_mul_f32_e32 v179, v179, v219
	v_cvt_pk_bf16_f32 v178, v178, v179
	v_cndmask_b32_e32 v145, 0, v145, vcc
	v_cmp_le_i32_e32 vcc, v194, v197
	s_nop 1
	v_cndmask_b32_e32 v144, 0, v144, vcc
	v_pk_mul_f32 v[144:145], v[144:145], v[220:221]
	s_nop 0
	v_cvt_pk_bf16_f32 v179, v144, v145
	s_waitcnt lgkmcnt(2)
	v_add_f32_e32 v144, v222, v242
	v_mul_f32_e32 v144, 0x3fb8aa3b, v144
	v_add_u32_e32 v145, v180, v198
	v_exp_f32_e32 v144, v144
	ds_write_b64 v145, v[178:179]
	v_add_f32_e32 v145, v223, v242
	v_mul_f32_e32 v145, 0x3fb8aa3b, v145
	v_exp_f32_e32 v145, v145
	v_add_u32_e32 v178, s19, v138
	v_mul_f32_e32 v144, v234, v144
	v_cmp_le_i32_e32 vcc, v183, v178
	v_mul_f32_e32 v179, v235, v145
	v_add_f32_e32 v145, v225, v242
	v_cndmask_b32_e32 v144, 0, v144, vcc
	v_mul_f32_e32 v174, v144, v174
	v_add_f32_e32 v144, v224, v242
	v_mul_f32_e32 v144, 0x3fb8aa3b, v144
	v_mul_f32_e32 v145, 0x3fb8aa3b, v145
	v_exp_f32_e32 v144, v144
	v_exp_f32_e32 v145, v145
	v_cmp_lt_i32_e32 vcc, v183, v178
	v_pk_mul_f32 v[144:145], v[236:237], v[144:145]
	s_nop 0
	v_cndmask_b32_e32 v179, 0, v179, vcc
	v_cmp_le_i32_e32 vcc, v181, v178
	v_mul_f32_e32 v175, v179, v175
	v_cvt_pk_bf16_f32 v174, v174, v175
	v_cndmask_b32_e32 v145, 0, v145, vcc
	v_cmp_le_i32_e32 vcc, v194, v178
	v_or_b32_e32 v179, 3, v238
	s_nop 0
	v_cndmask_b32_e32 v144, 0, v144, vcc
	v_pk_mul_f32 v[144:145], v[144:145], v[176:177]
	v_mul_lo_u32 v176, v178, s88
	v_cvt_pk_bf16_f32 v175, v144, v145
	v_add_f32_e32 v144, v84, v239
	v_mul_f32_e32 v144, 0x3fb8aa3b, v144
	v_add_u32_e32 v145, v180, v176
	v_exp_f32_e32 v144, v144
	ds_write_b64 v145, v[174:175]
	v_add_f32_e32 v145, v85, v239
	v_mul_f32_e32 v145, 0x3fb8aa3b, v145
	v_exp_f32_e32 v145, v145
	v_mul_f32_e32 v144, v80, v144
	v_cmp_le_i32_e32 vcc, v238, v173
	v_or_b32_e32 v180, 2, v238
	v_lshl_add_u32 v177, v238, 1, s83
	v_cndmask_b32_e32 v144, 0, v144, vcc
	v_mul_f32_e32 v174, v144, v190
	v_mul_f32_e32 v144, v81, v145
	v_cmp_lt_i32_e32 vcc, v238, v173
	v_add_f32_e32 v145, v87, v239
	v_mul_f32_e32 v145, 0x3fb8aa3b, v145
	v_cndmask_b32_e32 v175, 0, v144, vcc
	v_add_f32_e32 v144, v86, v239
	v_mul_f32_e32 v144, 0x3fb8aa3b, v144
	v_exp_f32_e32 v144, v144
	v_exp_f32_e32 v145, v145
	v_cmp_le_i32_e32 vcc, v179, v173
	v_mul_f32_e32 v175, v175, v191
	v_cvt_pk_bf16_f32 v174, v174, v175
	v_pk_mul_f32 v[144:145], v[82:83], v[144:145]
	s_nop 0
	v_cndmask_b32_e32 v145, 0, v145, vcc
	v_cmp_le_i32_e32 vcc, v180, v173
	v_add_f32_e32 v173, v84, v240
	v_mul_f32_e32 v173, 0x3fb8aa3b, v173
	v_cndmask_b32_e32 v144, 0, v144, vcc
	v_pk_mul_f32 v[144:145], v[144:145], v[192:193]
	v_exp_f32_e32 v173, v173
	v_cvt_pk_bf16_f32 v175, v144, v145
	v_add_f32_e32 v145, v85, v240
	v_mul_f32_e32 v145, 0x3fb8aa3b, v145
	v_exp_f32_e32 v145, v145
	v_add_u32_e32 v144, v177, v182
	ds_write_b64 v144, v[174:175]
	v_mul_f32_e32 v144, v80, v173
	v_cmp_le_i32_e32 vcc, v238, v195
	s_nop 1
	v_cndmask_b32_e32 v144, 0, v144, vcc
	v_mul_f32_e32 v173, v144, v96
	v_mul_f32_e32 v96, v81, v145
	v_add_f32_e32 v144, v86, v240
	v_add_f32_e32 v145, v87, v240
	v_mul_f32_e32 v144, 0x3fb8aa3b, v144
	v_mul_f32_e32 v145, 0x3fb8aa3b, v145
	v_exp_f32_e32 v144, v144
	v_exp_f32_e32 v145, v145
	v_cmp_lt_i32_e32 vcc, v238, v195
	s_nop 1
	v_cndmask_b32_e32 v96, 0, v96, vcc
	v_mul_f32_e32 v174, v96, v97
	v_pk_mul_f32 v[96:97], v[82:83], v[144:145]
	v_cmp_le_i32_e32 vcc, v179, v195
	s_nop 1
	v_cndmask_b32_e32 v97, 0, v97, vcc
	v_cmp_le_i32_e32 vcc, v180, v195
	s_nop 1
	v_cndmask_b32_e32 v96, 0, v96, vcc
	v_pk_mul_f32 v[96:97], v[96:97], v[98:99]
	v_add_f32_e32 v99, v84, v241
	v_mul_f32_e32 v99, 0x3fb8aa3b, v99
	v_exp_f32_e32 v144, v99
	v_cvt_pk_bf16_f32 v99, v96, v97
	v_add_f32_e32 v97, v85, v241
	v_mul_f32_e32 v97, 0x3fb8aa3b, v97
	v_exp_f32_e32 v97, v97
	v_cvt_pk_bf16_f32 v98, v173, v174
	v_add_u32_e32 v96, v177, v196
	ds_write_b64 v96, v[98:99]
	v_mul_f32_e32 v96, v80, v144
	v_cmp_le_i32_e32 vcc, v238, v197
	v_add_f32_e32 v84, v84, v242
	v_mul_f32_e32 v84, 0x3fb8aa3b, v84
	v_cndmask_b32_e32 v96, 0, v96, vcc
	v_mul_f32_e32 v98, v96, v92
	v_mul_f32_e32 v92, v81, v97
	v_add_f32_e32 v96, v86, v241
	v_add_f32_e32 v97, v87, v241
	v_exp_f32_e32 v84, v84
	v_mul_f32_e32 v96, 0x3fb8aa3b, v96
	v_mul_f32_e32 v97, 0x3fb8aa3b, v97
	v_exp_f32_e32 v96, v96
	v_exp_f32_e32 v97, v97
	v_cmp_lt_i32_e32 vcc, v238, v197
	v_mul_f32_e32 v80, v80, v84
	v_add_f32_e32 v84, v85, v242
	v_cndmask_b32_e32 v92, 0, v92, vcc
	v_mul_f32_e32 v84, 0x3fb8aa3b, v84
	v_mul_f32_e32 v99, v92, v93
	v_pk_mul_f32 v[92:93], v[82:83], v[96:97]
	v_cmp_le_i32_e32 vcc, v179, v197
	v_exp_f32_e32 v84, v84
	s_nop 0
	v_cndmask_b32_e32 v93, 0, v93, vcc
	v_cmp_le_i32_e32 vcc, v180, v197
	v_mul_f32_e32 v84, v81, v84
	v_add_f32_e32 v81, v87, v242
	v_cndmask_b32_e32 v92, 0, v92, vcc
	v_cmp_le_i32_e32 vcc, v238, v178
	v_mul_f32_e32 v81, 0x3fb8aa3b, v81
	v_exp_f32_e32 v81, v81
	v_cndmask_b32_e32 v80, 0, v80, vcc
	v_mul_f32_e32 v85, v80, v88
	v_add_f32_e32 v80, v86, v242
	v_mul_f32_e32 v80, 0x3fb8aa3b, v80
	v_exp_f32_e32 v80, v80
	v_cmp_lt_i32_e32 vcc, v238, v178
	v_pk_mul_f32 v[92:93], v[92:93], v[94:95]
	v_cvt_pk_bf16_f32 v94, v98, v99
	v_cndmask_b32_e32 v84, 0, v84, vcc
	v_pk_mul_f32 v[80:81], v[82:83], v[80:81]
	v_cmp_le_i32_e32 vcc, v179, v178
	v_mul_f32_e32 v84, v84, v89
	v_cvt_pk_bf16_f32 v82, v85, v84
	v_cndmask_b32_e32 v81, 0, v81, vcc
	v_cmp_le_i32_e32 vcc, v180, v178
	v_cvt_pk_bf16_f32 v95, v92, v93
	v_add_u32_e32 v92, v177, v198
	v_cndmask_b32_e32 v80, 0, v80, vcc
	v_pk_mul_f32 v[80:81], v[80:81], v[90:91]
	ds_write_b64 v92, v[94:95]
	v_cvt_pk_bf16_f32 v83, v80, v81
	v_add_u32_e32 v80, v177, v176
	ds_write_b64 v80, v[82:83]
	v_ashrrev_i32_e32 v80, 2, v138
	v_lshl_add_u32 v173, v133, 3, v80
	v_lshlrev_b32_e32 v80, 3, v138
	v_and_b32_e32 v80, 24, v80
	v_mul_lo_u32 v81, v173, s89
	v_add_u32_e32 v138, 0x12000, v143
	v_add_u32_e32 v82, v138, v142
	v_add3_u32 v182, 0, v81, v80
	s_waitcnt lgkmcnt(0)
	s_barrier
	v_add_u32_e32 v210, 0x1b000, v182
	ds_read_b128 v[88:91], v82
	ds_read_b64_tr_b16 v[92:93], v210
	ds_read_b64_tr_b16 v[94:95], v210 offset:640
	ds_read_b64_tr_b16 v[96:97], v210 offset:32
	ds_read_b64_tr_b16 v[142:143], v210 offset:64
	ds_read_b64_tr_b16 v[174:175], v210 offset:96
	ds_read_b64_tr_b16 v[98:99], v210 offset:672
	ds_read_b64_tr_b16 v[144:145], v210 offset:704
	ds_read_b64_tr_b16 v[176:177], v210 offset:736
	v_pk_mul_f32 v[82:83], v[54:55], v[0:1] op_sel_hi:[1,0]
	v_pk_mul_f32 v[80:81], v[52:53], v[0:1] op_sel_hi:[1,0]
	v_pk_mul_f32 v[86:87], v[50:51], v[0:1] op_sel_hi:[1,0]
	v_pk_mul_f32 v[84:85], v[48:49], v[0:1] op_sel_hi:[1,0]
	v_pk_mul_f32 v[54:55], v[58:59], v[0:1] op_sel_hi:[1,0]
	v_pk_mul_f32 v[52:53], v[56:57], v[0:1] op_sel_hi:[1,0]
	v_pk_mul_f32 v[50:51], v[62:63], v[0:1] op_sel_hi:[1,0]
	v_pk_mul_f32 v[48:49], v[60:61], v[0:1] op_sel_hi:[1,0]
	v_add_u32_e32 v0, v138, v141
	ds_read_b128 v[56:59], v0
	ds_read_b64_tr_b16 v[62:63], v210 offset:5760
	ds_read_b64_tr_b16 v[60:61], v210 offset:5120
	ds_read_b64_tr_b16 v[178:179], v210 offset:5152
	ds_read_b64_tr_b16 v[180:181], v210 offset:5792
	ds_read_b64_tr_b16 v[190:191], v210 offset:5184
	ds_read_b64_tr_b16 v[192:193], v210 offset:5824
	ds_read_b64_tr_b16 v[194:195], v210 offset:5216
	ds_read_b64_tr_b16 v[196:197], v210 offset:5856
	s_waitcnt lgkmcnt(14)
	v_mfma_f32_16x16x32_bf16 v[72:75], v[92:95], v[88:91], v[72:75]
	s_waitcnt lgkmcnt(11)
	v_mfma_f32_16x16x32_bf16 v[76:79], v[96:99], v[88:91], v[76:79]
	s_waitcnt lgkmcnt(10)
	v_mfma_f32_16x16x32_bf16 v[68:71], v[142:145], v[88:91], v[68:71]
	s_waitcnt lgkmcnt(9)
	v_mfma_f32_16x16x32_bf16 v[64:67], v[174:177], v[88:91], v[64:67]
	v_add_u32_e32 v0, v138, v140
	ds_read_b128 v[88:91], v0
	ds_read_b64_tr_b16 v[92:93], v210 offset:10240
	ds_read_b64_tr_b16 v[96:97], v210 offset:10272
	ds_read_b64_tr_b16 v[140:141], v210 offset:10304
	ds_read_b64_tr_b16 v[174:175], v210 offset:10336
	ds_read_b64_tr_b16 v[94:95], v210 offset:10880
	ds_read_b64_tr_b16 v[98:99], v210 offset:10912
	ds_read_b64_tr_b16 v[142:143], v210 offset:10944
	ds_read_b64_tr_b16 v[176:177], v210 offset:10976
	s_waitcnt lgkmcnt(14)
	v_mfma_f32_16x16x32_bf16 v[60:63], v[60:63], v[56:59], v[72:75]
	s_waitcnt lgkmcnt(13)
	v_mfma_f32_16x16x32_bf16 v[72:75], v[178:181], v[56:59], v[76:79]
	s_waitcnt lgkmcnt(11)
	v_mfma_f32_16x16x32_bf16 v[68:71], v[190:193], v[56:59], v[68:71]
	s_waitcnt lgkmcnt(9)
	v_mfma_f32_16x16x32_bf16 v[56:59], v[194:197], v[56:59], v[64:67]
	v_add_u32_e32 v0, v138, v139
	s_nop 1
	ds_read_b128 v[64:67], v0
	ds_read_b64_tr_b16 v[76:77], v210 offset:15360
	ds_read_b64_tr_b16 v[178:179], v210 offset:15392
	ds_read_b64_tr_b16 v[190:191], v210 offset:15424
	ds_read_b64_tr_b16 v[194:195], v210 offset:15456
	ds_read_b64_tr_b16 v[78:79], v210 offset:16000
	ds_read_b64_tr_b16 v[180:181], v210 offset:16032
	ds_read_b64_tr_b16 v[192:193], v210 offset:16064
	ds_read_b64_tr_b16 v[196:197], v210 offset:16096
	s_waitcnt lgkmcnt(12)
	v_mfma_f32_16x16x32_bf16 v[60:63], v[92:95], v[88:91], v[60:63]
	s_waitcnt lgkmcnt(9)
	v_mfma_f32_16x16x32_bf16 v[56:59], v[174:177], v[88:91], v[56:59]
	v_mfma_f32_16x16x32_bf16 v[72:75], v[96:99], v[88:91], v[72:75]
	v_mfma_f32_16x16x32_bf16 v[68:71], v[140:143], v[88:91], v[68:71]
	v_lshlrev_b32_e32 v0, 7, v173
	v_lshl_add_u32 v173, v133, 5, 0
	v_add3_u32 v0, v182, v0, s87
	v_add_u32_e32 v92, 0x26200, v173
	ds_read_b64_tr_b16 v[182:183], v0 offset:36864
	ds_read_b64_tr_b16 v[202:203], v0 offset:38016
	ds_read_b128 v[88:91], v92
	ds_read_b128 v[92:95], v92 offset:16
	ds_read_b64_tr_b16 v[96:97], v210
	ds_read_b64_tr_b16 v[138:139], v210 offset:32
	ds_read_b64_tr_b16 v[142:143], v210 offset:64
	ds_read_b64_tr_b16 v[174:175], v210 offset:96
	ds_read_b64_tr_b16 v[98:99], v210 offset:640
	ds_read_b64_tr_b16 v[140:141], v210 offset:672
	ds_read_b64_tr_b16 v[144:145], v210 offset:704
	ds_read_b64_tr_b16 v[176:177], v210 offset:736
	v_add_u32_e32 v211, 0x9000, v0
	s_waitcnt lgkmcnt(14)
	v_mfma_f32_16x16x32_bf16 v[60:63], v[76:79], v[64:67], v[60:63]
	s_waitcnt lgkmcnt(12)
	v_mfma_f32_16x16x32_bf16 v[56:59], v[194:197], v[64:67], v[56:59]
	v_mfma_f32_16x16x32_bf16 v[72:75], v[178:181], v[64:67], v[72:75]
	v_mfma_f32_16x16x32_bf16 v[68:71], v[190:193], v[64:67], v[68:71]
	v_add_u32_e32 v76, 0x26280, v173
	ds_read_b64_tr_b16 v[204:205], v0 offset:46080
	ds_read_b64_tr_b16 v[206:207], v0 offset:47232
	ds_read_b128 v[64:67], v76
	ds_read_b128 v[76:79], v76 offset:16
	ds_read_b64_tr_b16 v[178:179], v210 offset:5120
	ds_read_b64_tr_b16 v[190:191], v210 offset:5152
	ds_read_b64_tr_b16 v[194:195], v210 offset:5184
	ds_read_b64_tr_b16 v[198:199], v210 offset:5216
	ds_read_b64_tr_b16 v[180:181], v210 offset:5760
	ds_read_b64_tr_b16 v[192:193], v210 offset:5792
	ds_read_b64_tr_b16 v[196:197], v210 offset:5824
	ds_read_b64_tr_b16 v[200:201], v210 offset:5856
	s_waitcnt lgkmcnt(14)
	v_lshlrev_b32_e32 v208, 16, v182
	v_and_b32_e32 v209, 0xffff0000, v182
	v_lshlrev_b32_e32 v182, 16, v183
	v_and_b32_e32 v183, 0xffff0000, v183
	v_pk_mul_f32 v[88:89], v[88:89], v[208:209]
	v_pk_mul_f32 v[90:91], v[90:91], v[182:183]
	v_cvt_pk_bf16_f32 v88, v88, v89
	v_cvt_pk_bf16_f32 v89, v90, v91
	v_lshlrev_b32_e32 v90, 16, v202
	v_and_b32_e32 v91, 0xffff0000, v202
	v_pk_mul_f32 v[90:91], v[92:93], v[90:91]
	v_lshlrev_b32_e32 v92, 16, v203
	v_and_b32_e32 v93, 0xffff0000, v203
	v_pk_mul_f32 v[92:93], v[94:95], v[92:93]
	v_cvt_pk_bf16_f32 v90, v90, v91
	v_cvt_pk_bf16_f32 v91, v92, v93
	s_waitcnt lgkmcnt(13)
	s_nop 0
	v_mfma_f32_16x16x32_bf16 v[52:55], v[88:91], v[142:145], v[52:55]
	s_waitcnt lgkmcnt(12)
	v_mfma_f32_16x16x32_bf16 v[48:51], v[88:91], v[174:177], v[48:51]
	v_mfma_f32_16x16x32_bf16 v[80:83], v[88:91], v[96:99], v[80:83]
	v_mfma_f32_16x16x32_bf16 v[84:87], v[88:91], v[138:141], v[84:87]
	v_sub_u32_e32 v88, 0x7f, v137
	v_cndmask_b32_e64 v88, v88, v137, s[14:15]
	v_add_u32_e32 v88, s82, v88
	v_ashrrev_i32_e32 v89, 31, v88
	v_lshlrev_b64 v[88:89], 11, v[88:89]
	v_lshl_add_u64 v[88:89], s[78:79], 0, v[88:89]
	v_ashrrev_i32_e32 v133, 31, v132
	v_lshl_add_u64 v[88:89], v[132:133], 1, v[88:89]
	v_cvt_pk_bf16_f32 v60, v60, v61
	v_cvt_pk_bf16_f32 v61, v62, v63
	global_store_dwordx2 v[88:89], v[60:61], off sc1
	v_cvt_pk_bf16_f32 v60, v72, v73
	v_cvt_pk_bf16_f32 v61, v74, v75
	global_store_dwordx2 v[88:89], v[60:61], off offset:32 sc1
	v_cvt_pk_bf16_f32 v60, v68, v69
	v_cvt_pk_bf16_f32 v61, v70, v71
	v_cvt_pk_bf16_f32 v56, v56, v57
	v_cvt_pk_bf16_f32 v57, v58, v59
	global_store_dwordx2 v[88:89], v[60:61], off offset:64 sc1
	global_store_dwordx2 v[88:89], v[56:57], off offset:96 sc1
	v_add_u32_e32 v60, 0x26300, v173
	ds_read_b64_tr_b16 v[182:183], v0 offset:55296
	ds_read_b64_tr_b16 v[202:203], v0 offset:56448
	ds_read_b128 v[56:59], v60
	ds_read_b128 v[60:63], v60 offset:16
	ds_read_b64_tr_b16 v[70:71], v210 offset:10880
	ds_read_b64_tr_b16 v[68:69], v210 offset:10240
	ds_read_b64_tr_b16 v[72:73], v210 offset:10272
	ds_read_b64_tr_b16 v[74:75], v210 offset:10912
	ds_read_b64_tr_b16 v[88:89], v210 offset:10304
	ds_read_b64_tr_b16 v[90:91], v210 offset:10944
	ds_read_b64_tr_b16 v[92:93], v210 offset:10336
	ds_read_b64_tr_b16 v[94:95], v210 offset:10976
	s_waitcnt lgkmcnt(14)
	v_lshlrev_b32_e32 v96, 16, v204
	v_and_b32_e32 v97, 0xffff0000, v204
	v_pk_mul_f32 v[64:65], v[64:65], v[96:97]
	v_lshlrev_b32_e32 v96, 16, v205
	v_and_b32_e32 v97, 0xffff0000, v205
	v_pk_mul_f32 v[66:67], v[66:67], v[96:97]
	v_cvt_pk_bf16_f32 v64, v64, v65
	v_cvt_pk_bf16_f32 v65, v66, v67
	v_lshlrev_b32_e32 v66, 16, v206
	v_and_b32_e32 v67, 0xffff0000, v206
	v_pk_mul_f32 v[66:67], v[76:77], v[66:67]
	v_lshlrev_b32_e32 v76, 16, v207
	v_and_b32_e32 v77, 0xffff0000, v207
	v_pk_mul_f32 v[76:77], v[78:79], v[76:77]
	v_cvt_pk_bf16_f32 v66, v66, v67
	v_cvt_pk_bf16_f32 v67, v76, v77
	s_waitcnt lgkmcnt(13)
	s_nop 0
	v_mfma_f32_16x16x32_bf16 v[52:55], v[64:67], v[194:197], v[52:55]
	s_waitcnt lgkmcnt(12)
	v_mfma_f32_16x16x32_bf16 v[48:51], v[64:67], v[198:201], v[48:51]
	v_mfma_f32_16x16x32_bf16 v[76:79], v[64:67], v[178:181], v[80:83]
	v_mfma_f32_16x16x32_bf16 v[80:83], v[64:67], v[190:193], v[84:87]
	ds_read_b64_tr_b16 v[178:179], v0 offset:64512
	ds_read_b64_tr_b16 v[180:181], v211 offset:28800
	v_add_u32_e32 v0, 0x26380, v173
	ds_read_b128 v[64:67], v0
	ds_read_b128 v[84:87], v0 offset:16
	ds_read_b64_tr_b16 v[96:97], v210 offset:15360
	ds_read_b64_tr_b16 v[138:139], v210 offset:15392
	ds_read_b64_tr_b16 v[142:143], v210 offset:15424
	ds_read_b64_tr_b16 v[174:175], v210 offset:15456
	ds_read_b64_tr_b16 v[98:99], v210 offset:16000
	ds_read_b64_tr_b16 v[140:141], v210 offset:16032
	ds_read_b64_tr_b16 v[144:145], v210 offset:16064
	ds_read_b64_tr_b16 v[176:177], v210 offset:16096
	s_waitcnt lgkmcnt(14)
	v_lshlrev_b32_e32 v190, 16, v182
	v_and_b32_e32 v191, 0xffff0000, v182
	v_lshlrev_b32_e32 v182, 16, v183
	v_and_b32_e32 v183, 0xffff0000, v183
	v_pk_mul_f32 v[56:57], v[56:57], v[190:191]
	v_pk_mul_f32 v[58:59], v[58:59], v[182:183]
	v_cvt_pk_bf16_f32 v56, v56, v57
	v_cvt_pk_bf16_f32 v57, v58, v59
	v_lshlrev_b32_e32 v58, 16, v202
	v_and_b32_e32 v59, 0xffff0000, v202
	v_pk_mul_f32 v[58:59], v[60:61], v[58:59]
	v_lshlrev_b32_e32 v60, 16, v203
	v_and_b32_e32 v61, 0xffff0000, v203
	v_pk_mul_f32 v[60:61], v[62:63], v[60:61]
	v_cvt_pk_bf16_f32 v58, v58, v59
	v_cvt_pk_bf16_f32 v59, v60, v61
	s_nop 1
	v_mfma_f32_16x16x32_bf16 v[60:63], v[56:59], v[68:71], v[76:79]
	v_mfma_f32_16x16x32_bf16 v[68:71], v[56:59], v[72:75], v[80:83]
	v_mfma_f32_16x16x32_bf16 v[72:75], v[56:59], v[88:91], v[52:55]
	s_waitcnt lgkmcnt(12)
	v_mfma_f32_16x16x32_bf16 v[76:79], v[56:59], v[92:95], v[48:51]
	s_waitcnt lgkmcnt(11)
	s_nop 1
	v_lshlrev_b32_e32 v48, 16, v178
	v_and_b32_e32 v49, 0xffff0000, v178
	s_waitcnt lgkmcnt(9)
	v_pk_mul_f32 v[48:49], v[64:65], v[48:49]
	s_add_i32 s23, s23, -1
	v_cvt_pk_bf16_f32 v64, v48, v49
	v_lshlrev_b32_e32 v48, 16, v179
	v_and_b32_e32 v49, 0xffff0000, v179
	v_pk_mul_f32 v[48:49], v[66:67], v[48:49]
	s_add_i32 s22, s22, 1
	v_cvt_pk_bf16_f32 v65, v48, v49
	v_lshlrev_b32_e32 v48, 16, v180
	v_and_b32_e32 v49, 0xffff0000, v180
	s_waitcnt lgkmcnt(8)
	v_pk_mul_f32 v[48:49], v[84:85], v[48:49]
	v_add_u32_e32 v0, s52, v132
	v_cvt_pk_bf16_f32 v66, v48, v49
	v_lshlrev_b32_e32 v48, 16, v181
	v_and_b32_e32 v49, 0xffff0000, v181
	v_pk_mul_f32 v[48:49], v[86:87], v[48:49]
	s_add_u32 s80, s80, 0x400
	v_cvt_pk_bf16_f32 v67, v48, v49
	v_lshl_add_u32 v0, v0, 1, v136
	s_addc_u32 s81, s81, 0
	s_waitcnt lgkmcnt(3)
	v_mfma_f32_16x16x32_bf16 v[52:55], v[64:67], v[96:99], v[60:63]
	s_cmp_eq_u32 s23, -2
	s_waitcnt lgkmcnt(2)
	v_mfma_f32_16x16x32_bf16 v[48:51], v[64:67], v[138:141], v[68:71]
	s_waitcnt lgkmcnt(1)
	v_mfma_f32_16x16x32_bf16 v[56:59], v[64:67], v[142:145], v[72:75]
	s_waitcnt lgkmcnt(0)
	v_mfma_f32_16x16x32_bf16 v[60:63], v[64:67], v[174:177], v[76:79]
	s_nop 0
	v_cvt_pk_bf16_f32 v64, v52, v53
	v_cvt_pk_bf16_f32 v65, v54, v55
	s_nop 0
	v_cvt_pk_bf16_f32 v66, v48, v49
	v_cvt_pk_bf16_f32 v67, v50, v51
	ds_write2st64_b64 v0, v[64:65], v[66:67] offset1:9
	v_cvt_pk_bf16_f32 v64, v56, v57
	v_cvt_pk_bf16_f32 v65, v58, v59
	v_cvt_pk_bf16_f32 v66, v60, v61
	v_cvt_pk_bf16_f32 v67, v62, v63
	ds_write2st64_b64 v0, v[64:65], v[66:67] offset0:18 offset1:27
	s_waitcnt lgkmcnt(0)
	s_barrier
	s_cbranch_scc1 .LBB0_608

.LBB0_631:
	s_add_i32 s23, s16, -1
	s_and_b64 s[78:79], s[12:13], exec
	v_add_u32_e32 v178, s52, v141
	s_cselect_b32 s22, s23, s22
	v_mul_lo_u32 v69, v178, s88
	v_mul_lo_u32 v70, v141, s88
	s_add_i32 s23, 0, 0x20000
	v_lshl_add_u32 v179, v178, 2, 0
	v_lshlrev_b32_e32 v180, 4, v142
	v_add_u32_e32 v181, 0, v69
	v_add_u32_e32 v177, s23, v70
	v_mov_b32_e32 v68, s10
	v_add_u32_e32 v71, 0x26000, v179
	v_add_u32_e32 v182, v181, v180
	v_add_u32_e32 v88, v177, v180
	s_waitcnt lgkmcnt(0)
	s_barrier
	ds_read_b64 v[128:129], v68
	ds_read_b32 v140, v71
	ds_read_b128 v[68:71], v182
	ds_read_b128 v[72:75], v88
	ds_read_b128 v[76:79], v88 offset:4608
	ds_read_b128 v[80:83], v88 offset:9216
	ds_read_b128 v[84:87], v88 offset:13824
	ds_read_b128 v[88:91], v88 offset:18432
	s_lshl_b32 s22, s22, 7
	v_add_u32_e32 v92, s91, v141
	v_add_u32_e32 v250, s92, v141
	s_add_i32 s22, s22, s82
	v_mul_lo_u32 v183, v92, s88
	v_mul_lo_u32 v251, v250, s88
	v_add_u32_e32 v145, 64, v180
	v_add_u32_e32 v143, v177, v145
	ds_read_b128 v[92:95], v182 offset:64
	ds_read_b128 v[96:99], v143
	ds_read_b128 v[100:103], v143 offset:4608
	ds_read_b128 v[104:107], v143 offset:9216
	ds_read_b128 v[190:193], v143 offset:13824
	ds_read_b128 v[194:197], v143 offset:18432
	s_waitcnt lgkmcnt(10)
	v_mfma_f32_16x16x32_bf16 v[72:75], v[72:75], v[68:71], 0
	s_waitcnt lgkmcnt(9)
	v_mfma_f32_16x16x32_bf16 v[76:79], v[76:79], v[68:71], 0
	s_waitcnt lgkmcnt(8)
	v_mfma_f32_16x16x32_bf16 v[80:83], v[80:83], v[68:71], 0
	s_waitcnt lgkmcnt(7)
	v_mfma_f32_16x16x32_bf16 v[84:87], v[84:87], v[68:71], 0
	s_waitcnt lgkmcnt(6)
	v_mfma_f32_16x16x32_bf16 v[68:71], v[88:91], v[68:71], 0
	v_add_u32_e32 v144, 0x80, v180
	v_add_u32_e32 v143, v177, v144
	ds_read_b128 v[88:91], v182 offset:128
	ds_read_b128 v[198:201], v143
	ds_read_b128 v[202:205], v143 offset:4608
	ds_read_b128 v[206:209], v143 offset:9216
	ds_read_b128 v[210:213], v143 offset:13824
	ds_read_b128 v[214:217], v143 offset:18432
	s_waitcnt lgkmcnt(10)
	v_mfma_f32_16x16x32_bf16 v[72:75], v[96:99], v[92:95], v[72:75]
	s_waitcnt lgkmcnt(9)
	v_mfma_f32_16x16x32_bf16 v[76:79], v[100:103], v[92:95], v[76:79]
	s_waitcnt lgkmcnt(8)
	v_mfma_f32_16x16x32_bf16 v[80:83], v[104:107], v[92:95], v[80:83]
	s_waitcnt lgkmcnt(7)
	v_mfma_f32_16x16x32_bf16 v[84:87], v[190:193], v[92:95], v[84:87]
	s_waitcnt lgkmcnt(6)
	v_mfma_f32_16x16x32_bf16 v[68:71], v[194:197], v[92:95], v[68:71]
	v_add_u32_e32 v143, 0xc0, v180
	v_add_u32_e32 v194, v177, v143
	ds_read_b128 v[92:95], v182 offset:192
	ds_read_b128 v[96:99], v194
	ds_read_b128 v[100:103], v194 offset:4608
	ds_read_b128 v[104:107], v194 offset:9216
	ds_read_b128 v[190:193], v194 offset:13824
	ds_read_b128 v[194:197], v194 offset:18432
	s_waitcnt lgkmcnt(10)
	v_mfma_f32_16x16x32_bf16 v[72:75], v[198:201], v[88:91], v[72:75]
	s_waitcnt lgkmcnt(9)
	v_mfma_f32_16x16x32_bf16 v[76:79], v[202:205], v[88:91], v[76:79]
	s_waitcnt lgkmcnt(8)
	v_mfma_f32_16x16x32_bf16 v[80:83], v[206:209], v[88:91], v[80:83]
	s_waitcnt lgkmcnt(7)
	v_mfma_f32_16x16x32_bf16 v[84:87], v[210:213], v[88:91], v[84:87]
	s_waitcnt lgkmcnt(6)
	v_mfma_f32_16x16x32_bf16 v[68:71], v[214:217], v[88:91], v[68:71]
	v_add3_u32 v182, 0, v183, v180
	v_add3_u32 v183, 0, v251, v180
	ds_read_b128 v[88:91], v182 offset:36864
	ds_read_b128 v[198:201], v182 offset:41472
	ds_read_b128 v[202:205], v183
	ds_read_b128 v[206:209], v183 offset:4608
	ds_read_b128 v[210:213], v183 offset:9216
	ds_read_b128 v[214:217], v183 offset:13824
	s_waitcnt lgkmcnt(10)
	v_mfma_f32_16x16x32_bf16 v[72:75], v[96:99], v[92:95], v[72:75]
	s_waitcnt lgkmcnt(9)
	v_mfma_f32_16x16x32_bf16 v[76:79], v[100:103], v[92:95], v[76:79]
	s_waitcnt lgkmcnt(8)
	v_mfma_f32_16x16x32_bf16 v[80:83], v[104:107], v[92:95], v[80:83]
	s_waitcnt lgkmcnt(7)
	v_mfma_f32_16x16x32_bf16 v[84:87], v[190:193], v[92:95], v[84:87]
	s_waitcnt lgkmcnt(6)
	v_mfma_f32_16x16x32_bf16 v[92:95], v[194:197], v[92:95], v[68:71]
	s_nop 2
	v_mul_f32_e64 v70, v140, v74
	v_mul_f32_e64 v71, v140, v75
	v_pk_mul_f32 v[68:69], v[140:141], v[72:73] op_sel_hi:[0,1]
	v_pk_mul_f32 v[74:75], v[140:141], v[78:79] op_sel_hi:[0,1]
	v_pk_mul_f32 v[72:73], v[140:141], v[76:77] op_sel_hi:[0,1]
	v_pk_mul_f32 v[78:79], v[140:141], v[82:83] op_sel_hi:[0,1]
	v_pk_mul_f32 v[76:77], v[140:141], v[80:81] op_sel_hi:[0,1]
	v_pk_mul_f32 v[82:83], v[140:141], v[86:87] op_sel_hi:[0,1]
	v_pk_mul_f32 v[80:81], v[140:141], v[84:85] op_sel_hi:[0,1]
	v_pk_mul_f32 v[86:87], v[140:141], v[94:95] op_sel_hi:[0,1]
	v_pk_mul_f32 v[84:85], v[140:141], v[92:93] op_sel_hi:[0,1]
	ds_read_b128 v[92:95], v182 offset:36928
	ds_read_b128 v[96:99], v182 offset:41536
	ds_read_b128 v[100:103], v183 offset:64
	ds_read_b128 v[104:107], v183 offset:4672
	ds_read_b128 v[190:193], v183 offset:9280
	ds_read_b128 v[194:197], v183 offset:13888
	s_waitcnt lgkmcnt(9)
	v_mfma_f32_16x16x32_bf16 v[218:221], v[88:91], v[202:205], 0
	s_waitcnt lgkmcnt(8)
	v_mfma_f32_16x16x32_bf16 v[222:225], v[88:91], v[206:209], 0
	s_waitcnt lgkmcnt(7)
	v_mfma_f32_16x16x32_bf16 v[226:229], v[88:91], v[210:213], 0
	s_waitcnt lgkmcnt(6)
	v_mfma_f32_16x16x32_bf16 v[88:91], v[88:91], v[214:217], 0
	v_mfma_f32_16x16x32_bf16 v[202:205], v[198:201], v[202:205], 0
	v_mfma_f32_16x16x32_bf16 v[206:209], v[198:201], v[206:209], 0
	v_mfma_f32_16x16x32_bf16 v[210:213], v[198:201], v[210:213], 0
	v_mfma_f32_16x16x32_bf16 v[198:201], v[198:201], v[214:217], 0
	ds_read_b128 v[214:217], v182 offset:36992
	ds_read_b128 v[230:233], v182 offset:41600
	ds_read_b128 v[234:237], v183 offset:128
	ds_read_b128 v[238:241], v183 offset:4736
	ds_read_b128 v[242:245], v183 offset:9344
	ds_read_b128 v[246:249], v183 offset:13952
	s_waitcnt lgkmcnt(9)
	v_mfma_f32_16x16x32_bf16 v[218:221], v[92:95], v[100:103], v[218:221]
	s_waitcnt lgkmcnt(8)
	v_mfma_f32_16x16x32_bf16 v[222:225], v[92:95], v[104:107], v[222:225]
	s_waitcnt lgkmcnt(7)
	v_mfma_f32_16x16x32_bf16 v[226:229], v[92:95], v[190:193], v[226:229]
	s_waitcnt lgkmcnt(6)
	v_mfma_f32_16x16x32_bf16 v[88:91], v[92:95], v[194:197], v[88:91]
	v_mfma_f32_16x16x32_bf16 v[92:95], v[96:99], v[100:103], v[202:205]
	v_mfma_f32_16x16x32_bf16 v[100:103], v[96:99], v[104:107], v[206:209]
	v_mfma_f32_16x16x32_bf16 v[104:107], v[96:99], v[190:193], v[210:213]
	v_mfma_f32_16x16x32_bf16 v[96:99], v[96:99], v[194:197], v[198:201]
	ds_read_b128 v[190:193], v182 offset:37056
	ds_read_b128 v[194:197], v182 offset:41664
	s_nop 0
	ds_read_b128 v[198:201], v183 offset:192
	ds_read_b128 v[202:205], v183 offset:4800
	ds_read_b128 v[206:209], v183 offset:9408
	ds_read_b128 v[210:213], v183 offset:14016
	s_waitcnt lgkmcnt(9)
	v_mfma_f32_16x16x32_bf16 v[218:221], v[214:217], v[234:237], v[218:221]
	s_waitcnt lgkmcnt(8)
	v_mfma_f32_16x16x32_bf16 v[222:225], v[214:217], v[238:241], v[222:225]
	s_waitcnt lgkmcnt(7)
	v_mfma_f32_16x16x32_bf16 v[226:229], v[214:217], v[242:245], v[226:229]
	s_waitcnt lgkmcnt(6)
	v_mfma_f32_16x16x32_bf16 v[214:217], v[214:217], v[246:249], v[88:91]
	v_mfma_f32_16x16x32_bf16 v[234:237], v[230:233], v[234:237], v[92:95]
	v_mfma_f32_16x16x32_bf16 v[100:103], v[230:233], v[238:241], v[100:103]
	v_mfma_f32_16x16x32_bf16 v[238:241], v[230:233], v[242:245], v[104:107]
	v_mfma_f32_16x16x32_bf16 v[96:99], v[230:233], v[246:249], v[96:99]
	v_lshlrev_b32_e32 v140, 2, v142
	v_add_u32_e32 v246, s91, v140
	s_add_i32 s23, 0, 0x25c00
	v_lshlrev_b32_e32 v88, 2, v246
	s_add_i32 s26, 0, 0x25e00
	v_add_u32_e32 v89, s23, v88
	v_add_u32_e32 v88, s26, v88
	v_add_u32_e32 v247, s93, v140
	ds_read_b128 v[230:233], v89
	ds_read_b128 v[242:245], v88
	v_lshlrev_b32_e32 v88, 2, v247
	v_add_u32_e32 v89, s23, v88
	s_add_i32 s23, 0, 0x25a00
	v_lshl_add_u32 v104, v141, 2, s23
	v_add_u32_e32 v88, s26, v88
	v_add_u32_e32 v105, s94, v104
	ds_read_b128 v[92:95], v89
	ds_read_b128 v[88:91], v88
	v_add_u32_e32 v106, s95, v104
	v_add_u32_e32 v107, s96, v104
	v_add_u32_e32 v104, s97, v104
	ds_read_b32 v248, v105
	ds_read_b32 v249, v106
	ds_read_b32 v252, v107
	ds_read_b32 v253, v104
	s_waitcnt lgkmcnt(11)
	v_mfma_f32_16x16x32_bf16 v[218:221], v[190:193], v[198:201], v[218:221]
	s_waitcnt lgkmcnt(10)
	v_mfma_f32_16x16x32_bf16 v[222:225], v[190:193], v[202:205], v[222:225]
	s_waitcnt lgkmcnt(9)
	v_mfma_f32_16x16x32_bf16 v[226:229], v[190:193], v[206:209], v[226:229]
	s_waitcnt lgkmcnt(8)
	v_mfma_f32_16x16x32_bf16 v[190:193], v[190:193], v[210:213], v[214:217]
	v_mfma_f32_16x16x32_bf16 v[198:201], v[194:197], v[198:201], v[234:237]
	v_mfma_f32_16x16x32_bf16 v[104:107], v[194:197], v[202:205], v[100:103]
	v_mfma_f32_16x16x32_bf16 v[100:103], v[194:197], v[206:209], v[238:241]
	v_mfma_f32_16x16x32_bf16 v[96:99], v[194:197], v[210:213], v[96:99]
	s_waitcnt lgkmcnt(3)
	v_add_f32_e32 v182, v230, v248
	v_mul_f32_e32 v182, 0x3fb8aa3b, v182
	v_exp_f32_e32 v182, v182
	v_add_f32_e32 v183, v231, v248
	v_mul_f32_e32 v183, 0x3fb8aa3b, v183
	v_exp_f32_e32 v183, v183
	v_mul_f32_e32 v182, v242, v182
	v_cmp_le_i32_e32 vcc, v246, v250
	v_or_b32_e32 v197, 3, v246
	v_or_b32_e32 v202, 2, v246
	v_cndmask_b32_e32 v182, 0, v182, vcc
	v_mul_f32_e32 v194, v182, v218
	v_mul_f32_e32 v182, v243, v183
	v_cmp_lt_i32_e32 vcc, v246, v250
	v_add_f32_e32 v183, v233, v248
	v_mul_f32_e32 v183, 0x3fb8aa3b, v183
	v_cndmask_b32_e32 v195, 0, v182, vcc
	v_add_f32_e32 v182, v232, v248
	v_mul_f32_e32 v182, 0x3fb8aa3b, v182
	v_exp_f32_e32 v182, v182
	v_exp_f32_e32 v183, v183
	v_cmp_le_i32_e32 vcc, v197, v250
	s_add_i32 s23, 0, 0x12000
	v_mul_f32_e32 v195, v195, v219
	v_pk_mul_f32 v[182:183], v[244:245], v[182:183]
	v_lshl_add_u32 v196, v246, 1, s23
	v_cndmask_b32_e32 v183, 0, v183, vcc
	v_cmp_le_i32_e32 vcc, v202, v250
	v_cvt_pk_bf16_f32 v194, v194, v195
	v_add_u32_e32 v203, s3, v141
	v_cndmask_b32_e32 v182, 0, v182, vcc
	v_pk_mul_f32 v[182:183], v[182:183], v[220:221]
	v_cmp_le_i32_e32 vcc, v246, v203
	v_cvt_pk_bf16_f32 v195, v182, v183
	s_waitcnt lgkmcnt(2)
	v_add_f32_e32 v182, v230, v249
	v_mul_f32_e32 v182, 0x3fb8aa3b, v182
	v_add_u32_e32 v183, v196, v251
	v_exp_f32_e32 v182, v182
	ds_write_b64 v183, v[194:195]
	v_add_f32_e32 v183, v231, v249
	v_mul_f32_e32 v183, 0x3fb8aa3b, v183
	v_exp_f32_e32 v183, v183
	v_mul_f32_e32 v182, v242, v182
	v_cndmask_b32_e32 v182, 0, v182, vcc
	v_mul_f32_e32 v194, v182, v222
	v_mul_f32_e32 v195, v243, v183
	v_add_f32_e32 v182, v232, v249
	v_add_f32_e32 v183, v233, v249
	v_mul_f32_e32 v182, 0x3fb8aa3b, v182
	v_mul_f32_e32 v183, 0x3fb8aa3b, v183
	v_exp_f32_e32 v182, v182
	v_exp_f32_e32 v183, v183
	v_cmp_lt_i32_e32 vcc, v246, v203
	v_mul_lo_u32 v204, v203, s88
	v_add_u32_e32 v205, s18, v141
	v_cndmask_b32_e32 v195, 0, v195, vcc
	v_pk_mul_f32 v[182:183], v[244:245], v[182:183]
	v_cmp_le_i32_e32 vcc, v197, v203
	v_mul_f32_e32 v195, v195, v223
	v_cvt_pk_bf16_f32 v194, v194, v195
	v_cndmask_b32_e32 v183, 0, v183, vcc
	v_cmp_le_i32_e32 vcc, v202, v203
	v_mul_lo_u32 v206, v205, s88
	v_add_u32_e32 v181, 0x12000, v181
	v_cndmask_b32_e32 v182, 0, v182, vcc
	v_pk_mul_f32 v[182:183], v[182:183], v[224:225]
	v_cmp_le_i32_e32 vcc, v246, v205
	v_cvt_pk_bf16_f32 v195, v182, v183
	s_waitcnt lgkmcnt(2)
	v_add_f32_e32 v182, v230, v252
	v_mul_f32_e32 v182, 0x3fb8aa3b, v182
	v_add_u32_e32 v183, v196, v204
	v_exp_f32_e32 v182, v182
	ds_write_b64 v183, v[194:195]
	v_add_f32_e32 v183, v231, v252
	v_mul_f32_e32 v183, 0x3fb8aa3b, v183
	v_exp_f32_e32 v183, v183
	v_mul_f32_e32 v182, v242, v182
	v_cndmask_b32_e32 v182, 0, v182, vcc
	v_mul_f32_e32 v194, v182, v226
	v_mul_f32_e32 v195, v243, v183
	v_add_f32_e32 v182, v232, v252
	v_add_f32_e32 v183, v233, v252
	v_mul_f32_e32 v182, 0x3fb8aa3b, v182
	v_mul_f32_e32 v183, 0x3fb8aa3b, v183
	v_exp_f32_e32 v182, v182
	v_exp_f32_e32 v183, v183
	v_cmp_lt_i32_e32 vcc, v246, v205
	v_pk_mul_f32 v[182:183], v[244:245], v[182:183]
	s_nop 0
	v_cndmask_b32_e32 v195, 0, v195, vcc
	v_cmp_le_i32_e32 vcc, v197, v205
	v_mul_f32_e32 v195, v195, v227
	v_cvt_pk_bf16_f32 v194, v194, v195
	v_cndmask_b32_e32 v183, 0, v183, vcc
	v_cmp_le_i32_e32 vcc, v202, v205
	s_nop 1
	v_cndmask_b32_e32 v182, 0, v182, vcc
	v_pk_mul_f32 v[182:183], v[182:183], v[228:229]
	s_nop 0
	v_cvt_pk_bf16_f32 v195, v182, v183
	s_waitcnt lgkmcnt(2)
	v_add_f32_e32 v182, v230, v253
	v_mul_f32_e32 v182, 0x3fb8aa3b, v182
	v_add_u32_e32 v183, v196, v206
	v_exp_f32_e32 v182, v182
	ds_write_b64 v183, v[194:195]
	v_add_f32_e32 v183, v231, v253
	v_mul_f32_e32 v183, 0x3fb8aa3b, v183
	v_exp_f32_e32 v183, v183
	v_add_u32_e32 v194, s19, v141
	v_mul_f32_e32 v182, v242, v182
	v_cmp_le_i32_e32 vcc, v246, v194
	v_mul_f32_e32 v195, v243, v183
	v_add_f32_e32 v183, v233, v253
	v_cndmask_b32_e32 v182, 0, v182, vcc
	v_mul_f32_e32 v190, v182, v190
	v_add_f32_e32 v182, v232, v253
	v_mul_f32_e32 v182, 0x3fb8aa3b, v182
	v_mul_f32_e32 v183, 0x3fb8aa3b, v183
	v_exp_f32_e32 v182, v182
	v_exp_f32_e32 v183, v183
	v_cmp_lt_i32_e32 vcc, v246, v194
	v_pk_mul_f32 v[182:183], v[244:245], v[182:183]
	s_nop 0
	v_cndmask_b32_e32 v195, 0, v195, vcc
	v_cmp_le_i32_e32 vcc, v197, v194
	v_mul_f32_e32 v191, v195, v191
	v_cvt_pk_bf16_f32 v190, v190, v191
	v_cndmask_b32_e32 v183, 0, v183, vcc
	v_cmp_le_i32_e32 vcc, v202, v194
	v_or_b32_e32 v195, 3, v247
	s_nop 0
	v_cndmask_b32_e32 v182, 0, v182, vcc
	v_pk_mul_f32 v[182:183], v[182:183], v[192:193]
	v_mul_lo_u32 v192, v194, s88
	v_cvt_pk_bf16_f32 v191, v182, v183
	v_add_f32_e32 v182, v92, v248
	v_mul_f32_e32 v182, 0x3fb8aa3b, v182
	v_add_u32_e32 v183, v196, v192
	v_exp_f32_e32 v182, v182
	ds_write_b64 v183, v[190:191]
	v_add_f32_e32 v183, v93, v248
	v_mul_f32_e32 v183, 0x3fb8aa3b, v183
	v_exp_f32_e32 v183, v183
	v_mul_f32_e32 v182, v88, v182
	v_cmp_le_i32_e32 vcc, v247, v250
	v_or_b32_e32 v196, 2, v247
	v_lshl_add_u32 v193, v247, 1, s23
	v_cndmask_b32_e32 v182, 0, v182, vcc
	v_mul_f32_e32 v190, v182, v198
	v_mul_f32_e32 v182, v89, v183
	v_cmp_lt_i32_e32 vcc, v247, v250
	v_add_f32_e32 v183, v95, v248
	v_mul_f32_e32 v183, 0x3fb8aa3b, v183
	v_cndmask_b32_e32 v191, 0, v182, vcc
	v_add_f32_e32 v182, v94, v248
	v_mul_f32_e32 v182, 0x3fb8aa3b, v182
	v_exp_f32_e32 v182, v182
	v_exp_f32_e32 v183, v183
	v_cmp_le_i32_e32 vcc, v195, v250
	v_mul_f32_e32 v191, v191, v199
	v_cvt_pk_bf16_f32 v190, v190, v191
	v_pk_mul_f32 v[182:183], v[90:91], v[182:183]
	v_add_f32_e32 v191, v92, v249
	v_cndmask_b32_e32 v183, 0, v183, vcc
	v_cmp_le_i32_e32 vcc, v196, v250
	v_mul_f32_e32 v191, 0x3fb8aa3b, v191
	v_exp_f32_e32 v197, v191
	v_cndmask_b32_e32 v182, 0, v182, vcc
	v_pk_mul_f32 v[182:183], v[182:183], v[200:201]
	v_cmp_le_i32_e32 vcc, v247, v203
	v_cvt_pk_bf16_f32 v191, v182, v183
	v_add_f32_e32 v183, v93, v249
	v_mul_f32_e32 v183, 0x3fb8aa3b, v183
	v_exp_f32_e32 v183, v183
	v_add_u32_e32 v182, v193, v251
	ds_write_b64 v182, v[190:191]
	v_mul_f32_e32 v182, v88, v197
	v_cndmask_b32_e32 v182, 0, v182, vcc
	v_mul_f32_e32 v190, v182, v104
	v_mul_f32_e32 v104, v89, v183
	v_add_f32_e32 v182, v94, v249
	v_add_f32_e32 v183, v95, v249
	v_mul_f32_e32 v182, 0x3fb8aa3b, v182
	v_mul_f32_e32 v183, 0x3fb8aa3b, v183
	v_exp_f32_e32 v182, v182
	v_exp_f32_e32 v183, v183
	v_cmp_lt_i32_e32 vcc, v247, v203
	s_nop 1
	v_cndmask_b32_e32 v104, 0, v104, vcc
	v_mul_f32_e32 v191, v104, v105
	v_pk_mul_f32 v[104:105], v[90:91], v[182:183]
	v_cmp_le_i32_e32 vcc, v195, v203
	s_nop 1
	v_cndmask_b32_e32 v105, 0, v105, vcc
	v_cmp_le_i32_e32 vcc, v196, v203
	s_nop 1
	v_cndmask_b32_e32 v104, 0, v104, vcc
	v_pk_mul_f32 v[104:105], v[104:105], v[106:107]
	v_add_f32_e32 v107, v92, v252
	v_mul_f32_e32 v107, 0x3fb8aa3b, v107
	v_exp_f32_e32 v182, v107
	v_cvt_pk_bf16_f32 v107, v104, v105
	v_add_f32_e32 v105, v93, v252
	v_mul_f32_e32 v105, 0x3fb8aa3b, v105
	v_exp_f32_e32 v105, v105
	v_cvt_pk_bf16_f32 v106, v190, v191
	v_add_u32_e32 v104, v193, v204
	ds_write_b64 v104, v[106:107]
	v_mul_f32_e32 v104, v88, v182
	v_cmp_le_i32_e32 vcc, v247, v205
	v_add_f32_e32 v92, v92, v253
	v_mul_f32_e32 v92, 0x3fb8aa3b, v92
	v_cndmask_b32_e32 v104, 0, v104, vcc
	v_mul_f32_e32 v106, v104, v100
	v_mul_f32_e32 v100, v89, v105
	v_add_f32_e32 v104, v94, v252
	v_add_f32_e32 v105, v95, v252
	v_exp_f32_e32 v92, v92
	v_mul_f32_e32 v104, 0x3fb8aa3b, v104
	v_mul_f32_e32 v105, 0x3fb8aa3b, v105
	v_exp_f32_e32 v104, v104
	v_exp_f32_e32 v105, v105
	v_cmp_lt_i32_e32 vcc, v247, v205
	v_mul_f32_e32 v88, v88, v92
	v_add_f32_e32 v92, v93, v253
	v_cndmask_b32_e32 v100, 0, v100, vcc
	v_mul_f32_e32 v92, 0x3fb8aa3b, v92
	v_mul_f32_e32 v107, v100, v101
	v_pk_mul_f32 v[100:101], v[90:91], v[104:105]
	v_cmp_le_i32_e32 vcc, v195, v205
	v_exp_f32_e32 v92, v92
	s_nop 0
	v_cndmask_b32_e32 v101, 0, v101, vcc
	v_cmp_le_i32_e32 vcc, v196, v205
	v_mul_f32_e32 v92, v89, v92
	v_add_f32_e32 v89, v95, v253
	v_cndmask_b32_e32 v100, 0, v100, vcc
	v_cmp_le_i32_e32 vcc, v247, v194
	v_mul_f32_e32 v89, 0x3fb8aa3b, v89
	v_exp_f32_e32 v89, v89
	v_cndmask_b32_e32 v88, 0, v88, vcc
	v_mul_f32_e32 v93, v88, v96
	v_add_f32_e32 v88, v94, v253
	v_mul_f32_e32 v88, 0x3fb8aa3b, v88
	v_exp_f32_e32 v88, v88
	v_cmp_lt_i32_e32 vcc, v247, v194
	v_pk_mul_f32 v[100:101], v[100:101], v[102:103]
	v_cvt_pk_bf16_f32 v102, v106, v107
	v_cndmask_b32_e32 v92, 0, v92, vcc
	v_pk_mul_f32 v[88:89], v[90:91], v[88:89]
	v_cmp_le_i32_e32 vcc, v195, v194
	v_mul_f32_e32 v92, v92, v97
	v_cvt_pk_bf16_f32 v90, v93, v92
	v_cndmask_b32_e32 v89, 0, v89, vcc
	v_cmp_le_i32_e32 vcc, v196, v194
	v_cvt_pk_bf16_f32 v103, v100, v101
	v_add_u32_e32 v100, v193, v206
	v_cndmask_b32_e32 v88, 0, v88, vcc
	v_pk_mul_f32 v[88:89], v[88:89], v[98:99]
	ds_write_b64 v100, v[102:103]
	v_cvt_pk_bf16_f32 v91, v88, v89
	v_add_u32_e32 v88, v193, v192
	ds_write_b64 v88, v[90:91]
	v_ashrrev_i32_e32 v88, 2, v141
	v_lshl_add_u32 v182, v142, 3, v88
	v_lshlrev_b32_e32 v88, 3, v141
	v_and_b32_e32 v88, 24, v88
	v_mul_lo_u32 v89, v182, s89
	v_add_u32_e32 v90, v181, v180
	v_add3_u32 v183, 0, v89, v88
	s_waitcnt lgkmcnt(0)
	s_barrier
	v_add_u32_e32 v180, 0x1b000, v183
	ds_read_b128 v[190:193], v90
	ds_read_b64_tr_b16 v[194:195], v180
	ds_read_b64_tr_b16 v[196:197], v180 offset:640
	ds_read_b64_tr_b16 v[200:201], v180 offset:672
	ds_read_b64_tr_b16 v[204:205], v180 offset:704
	ds_read_b64_tr_b16 v[208:209], v180 offset:736
	ds_read_b64_tr_b16 v[198:199], v180 offset:32
	ds_read_b64_tr_b16 v[202:203], v180 offset:64
	ds_read_b64_tr_b16 v[206:207], v180 offset:96
	ds_read_b64_tr_b16 v[210:211], v180 offset:128
	ds_read_b64_tr_b16 v[212:213], v180 offset:768
	v_pk_mul_f32 v[104:105], v[48:49], v[128:129] op_sel_hi:[1,0]
	v_add_u32_e32 v48, v181, v145
	v_pk_mul_f32 v[90:91], v[66:67], v[128:129] op_sel_hi:[1,0]
	v_pk_mul_f32 v[88:89], v[64:65], v[128:129] op_sel_hi:[1,0]
	v_pk_mul_f32 v[94:95], v[62:63], v[128:129] op_sel_hi:[1,0]
	v_pk_mul_f32 v[92:93], v[60:61], v[128:129] op_sel_hi:[1,0]
	v_pk_mul_f32 v[98:99], v[58:59], v[128:129] op_sel_hi:[1,0]
	v_pk_mul_f32 v[96:97], v[56:57], v[128:129] op_sel_hi:[1,0]
	v_pk_mul_f32 v[102:103], v[54:55], v[128:129] op_sel_hi:[1,0]
	v_pk_mul_f32 v[100:101], v[52:53], v[128:129] op_sel_hi:[1,0]
	v_pk_mul_f32 v[106:107], v[50:51], v[128:129] op_sel_hi:[1,0]
	ds_read_b128 v[48:51], v48
	ds_read_b64_tr_b16 v[54:55], v180 offset:5760
	ds_read_b64_tr_b16 v[52:53], v180 offset:5120
	ds_read_b64_tr_b16 v[56:57], v180 offset:5152
	ds_read_b64_tr_b16 v[58:59], v180 offset:5792
	ds_read_b64_tr_b16 v[60:61], v180 offset:5184
	ds_read_b64_tr_b16 v[62:63], v180 offset:5824
	ds_read_b64_tr_b16 v[64:65], v180 offset:5216
	ds_read_b64_tr_b16 v[66:67], v180 offset:5856
	ds_read_b64_tr_b16 v[214:215], v180 offset:5248
	ds_read_b64_tr_b16 v[216:217], v180 offset:5888
	s_waitcnt lgkmcnt(14)
	v_mfma_f32_16x16x32_bf16 v[68:71], v[194:197], v[190:193], v[68:71]
	v_mfma_f32_16x16x32_bf16 v[72:75], v[198:201], v[190:193], v[72:75]
	v_mfma_f32_16x16x32_bf16 v[76:79], v[202:205], v[190:193], v[76:79]
	s_waitcnt lgkmcnt(13)
	v_mfma_f32_16x16x32_bf16 v[80:83], v[206:209], v[190:193], v[80:83]
	s_waitcnt lgkmcnt(11)
	v_mfma_f32_16x16x32_bf16 v[84:87], v[210:213], v[190:193], v[84:87]
	v_add_u32_e32 v128, v181, v144
	ds_read_b128 v[190:193], v128
	ds_read_b64_tr_b16 v[194:195], v180 offset:10240
	ds_read_b64_tr_b16 v[198:199], v180 offset:10272
	ds_read_b64_tr_b16 v[202:203], v180 offset:10304
	ds_read_b64_tr_b16 v[206:207], v180 offset:10336
	ds_read_b64_tr_b16 v[196:197], v180 offset:10880
	ds_read_b64_tr_b16 v[200:201], v180 offset:10912
	ds_read_b64_tr_b16 v[204:205], v180 offset:10944
	ds_read_b64_tr_b16 v[210:211], v180 offset:10368
	ds_read_b64_tr_b16 v[208:209], v180 offset:10976
	ds_read_b64_tr_b16 v[212:213], v180 offset:11008
	s_waitcnt lgkmcnt(14)
	v_mfma_f32_16x16x32_bf16 v[52:55], v[52:55], v[48:51], v[68:71]
	v_mfma_f32_16x16x32_bf16 v[56:59], v[56:59], v[48:51], v[72:75]
	v_mfma_f32_16x16x32_bf16 v[60:63], v[60:63], v[48:51], v[76:79]
	s_waitcnt lgkmcnt(13)
	v_mfma_f32_16x16x32_bf16 v[64:67], v[64:67], v[48:51], v[80:83]
	s_waitcnt lgkmcnt(11)
	v_mfma_f32_16x16x32_bf16 v[48:51], v[214:217], v[48:51], v[84:87]
	v_add_u32_e32 v68, v181, v143
	ds_read_b128 v[68:71], v68
	ds_read_b64_tr_b16 v[72:73], v180 offset:15360
	ds_read_b64_tr_b16 v[76:77], v180 offset:15392
	ds_read_b64_tr_b16 v[80:81], v180 offset:15424
	ds_read_b64_tr_b16 v[84:85], v180 offset:15456
	ds_read_b64_tr_b16 v[74:75], v180 offset:16000
	ds_read_b64_tr_b16 v[78:79], v180 offset:16032
	ds_read_b64_tr_b16 v[82:83], v180 offset:16064
	ds_read_b64_tr_b16 v[214:215], v180 offset:15488
	ds_read_b64_tr_b16 v[86:87], v180 offset:16096
	ds_read_b64_tr_b16 v[216:217], v180 offset:16128
	s_waitcnt lgkmcnt(14)
	v_mfma_f32_16x16x32_bf16 v[52:55], v[194:197], v[190:193], v[52:55]
	v_mfma_f32_16x16x32_bf16 v[56:59], v[198:201], v[190:193], v[56:59]
	v_mfma_f32_16x16x32_bf16 v[60:63], v[202:205], v[190:193], v[60:63]
	s_waitcnt lgkmcnt(12)
	v_mfma_f32_16x16x32_bf16 v[64:67], v[206:209], v[190:193], v[64:67]
	s_waitcnt lgkmcnt(11)
	v_mfma_f32_16x16x32_bf16 v[48:51], v[210:213], v[190:193], v[48:51]
	v_lshl_add_u32 v181, v142, 5, 0
	v_lshlrev_b32_e32 v128, 7, v182
	v_add_u32_e32 v142, 0x26200, v181
	v_add3_u32 v128, v183, v128, s87
	ds_read_b128 v[190:193], v142
	ds_read_b128 v[194:197], v142 offset:16
	ds_read_b64_tr_b16 v[198:199], v180
	ds_read_b64_tr_b16 v[202:203], v180 offset:32
	ds_read_b64_tr_b16 v[206:207], v180 offset:64
	ds_read_b64_tr_b16 v[210:211], v180 offset:96
	ds_read_b64_tr_b16 v[200:201], v180 offset:640
	ds_read_b64_tr_b16 v[204:205], v180 offset:672
	ds_read_b64_tr_b16 v[208:209], v180 offset:704
	ds_read_b64_tr_b16 v[218:219], v180 offset:128
	ds_read_b64_tr_b16 v[238:239], v128 offset:36864
	ds_read_b64_tr_b16 v[240:241], v128 offset:38016
	ds_read_b64_tr_b16 v[212:213], v180 offset:736
	ds_read_b64_tr_b16 v[220:221], v180 offset:768
	v_add_u32_e32 v182, 0x9000, v128
	s_waitcnt lgkmcnt(14)
	v_mfma_f32_16x16x32_bf16 v[222:225], v[72:75], v[68:71], v[52:55]
	v_mfma_f32_16x16x32_bf16 v[226:229], v[76:79], v[68:71], v[56:59]
	v_mfma_f32_16x16x32_bf16 v[230:233], v[80:83], v[68:71], v[60:63]
	v_mfma_f32_16x16x32_bf16 v[234:237], v[84:87], v[68:71], v[64:67]
	v_mfma_f32_16x16x32_bf16 v[214:217], v[214:217], v[68:71], v[48:51]
	s_nop 2
	v_add_u32_e32 v48, 0x26280, v181
	ds_read_b128 v[68:71], v48
	ds_read_b128 v[56:59], v48 offset:16
	ds_read_b64_tr_b16 v[52:53], v180 offset:5120
	ds_read_b64_tr_b16 v[48:49], v180 offset:5152
	ds_read_b64_tr_b16 v[60:61], v180 offset:5184
	ds_read_b64_tr_b16 v[64:65], v180 offset:5216
	ds_read_b64_tr_b16 v[54:55], v180 offset:5760
	ds_read_b64_tr_b16 v[50:51], v180 offset:5792
	ds_read_b64_tr_b16 v[62:63], v180 offset:5824
	ds_read_b64_tr_b16 v[72:73], v180 offset:5248
	ds_read_b64_tr_b16 v[144:145], v128 offset:46080
	ds_read_b64_tr_b16 v[142:143], v128 offset:47232
	ds_read_b64_tr_b16 v[66:67], v180 offset:5856
	ds_read_b64_tr_b16 v[74:75], v180 offset:5888
	s_waitcnt lgkmcnt(14)
	v_lshlrev_b32_e32 v76, 16, v238
	v_and_b32_e32 v77, 0xffff0000, v238
	v_pk_mul_f32 v[76:77], v[190:191], v[76:77]
	s_nop 0
	v_cvt_pk_bf16_f32 v190, v76, v77
	v_lshlrev_b32_e32 v76, 16, v239
	v_and_b32_e32 v77, 0xffff0000, v239
	v_pk_mul_f32 v[76:77], v[192:193], v[76:77]
	s_nop 0
	v_cvt_pk_bf16_f32 v191, v76, v77
	v_lshlrev_b32_e32 v76, 16, v240
	v_and_b32_e32 v77, 0xffff0000, v240
	v_pk_mul_f32 v[76:77], v[194:195], v[76:77]
	s_nop 0
	v_cvt_pk_bf16_f32 v192, v76, v77
	v_lshlrev_b32_e32 v76, 16, v241
	v_and_b32_e32 v77, 0xffff0000, v241
	v_pk_mul_f32 v[76:77], v[196:197], v[76:77]
	s_nop 0
	v_cvt_pk_bf16_f32 v193, v76, v77
	s_nop 1
	v_mfma_f32_16x16x32_bf16 v[76:79], v[190:193], v[198:201], v[88:91]
	v_mfma_f32_16x16x32_bf16 v[80:83], v[190:193], v[202:205], v[92:95]
	v_mfma_f32_16x16x32_bf16 v[84:87], v[190:193], v[206:209], v[96:99]
	v_mfma_f32_16x16x32_bf16 v[88:91], v[190:193], v[210:213], v[100:103]
	v_mfma_f32_16x16x32_bf16 v[92:95], v[190:193], v[218:221], v[104:107]
	s_nop 0
	v_and_b32_e32 v96, 63, v141
	v_and_or_b32 v96, v172, 64, v96
	v_lshlrev_b32_e32 v96, 2, v96
	v_add_u32_e32 v97, 0x26400, v179
	ds_bpermute_b32 v96, v96, v214
	ds_read_b32 v97, v97
	v_ashrrev_i32_e32 v141, 31, v140
	v_add_u32_e32 v104, 0x26300, v181
	s_waitcnt lgkmcnt(1)
	v_max_f32_e64 v96, |v96|, |v96|
	s_waitcnt lgkmcnt(0)
	v_max_f32_e32 v97, v97, v97
	v_max_f32_e32 v96, v96, v97
	v_div_scale_f32 v97, s[78:79], v96, v96, 1.0
	v_rcp_f32_e32 v98, v97
	s_nop 0
	v_fma_f32 v99, -v97, v98, 1.0
	v_fmac_f32_e32 v98, v99, v98
	v_div_scale_f32 v99, vcc, 1.0, v96, 1.0
	v_mul_f32_e32 v100, v99, v98
	v_fma_f32 v101, -v97, v100, v99
	v_fmac_f32_e32 v100, v101, v98
	v_fma_f32 v97, -v97, v100, v99
	v_div_fmas_f32 v97, v97, v98, v100
	v_div_fixup_f32 v96, v97, v96, 1.0
	v_sub_u32_e32 v97, 0x7f, v178
	v_cndmask_b32_e64 v97, v97, v178, s[12:13]
	v_add_u32_e32 v98, s22, v97
	v_ashrrev_i32_e32 v99, 31, v98
	v_lshlrev_b64 v[98:99], 11, v[98:99]
	v_lshl_add_u64 v[98:99], s[74:75], 0, v[98:99]
	v_pk_mul_f32 v[100:101], v[222:223], v[96:97] op_sel_hi:[1,0]
	v_pk_mul_f32 v[102:103], v[224:225], v[96:97] op_sel_hi:[1,0]
	v_lshl_add_u64 v[98:99], v[140:141], 1, v[98:99]
	v_cvt_pk_bf16_f32 v100, v100, v101
	v_cvt_pk_bf16_f32 v101, v102, v103
	global_store_dwordx2 v[98:99], v[100:101], off sc1
	v_pk_mul_f32 v[100:101], v[226:227], v[96:97] op_sel_hi:[1,0]
	v_pk_mul_f32 v[102:103], v[228:229], v[96:97] op_sel_hi:[1,0]
	v_cvt_pk_bf16_f32 v100, v100, v101
	v_cvt_pk_bf16_f32 v101, v102, v103
	global_store_dwordx2 v[98:99], v[100:101], off offset:32 sc1
	v_pk_mul_f32 v[100:101], v[230:231], v[96:97] op_sel_hi:[1,0]
	v_pk_mul_f32 v[102:103], v[232:233], v[96:97] op_sel_hi:[1,0]
	v_cvt_pk_bf16_f32 v100, v100, v101
	v_cvt_pk_bf16_f32 v101, v102, v103
	global_store_dwordx2 v[98:99], v[100:101], off offset:64 sc1
	v_pk_mul_f32 v[100:101], v[234:235], v[96:97] op_sel_hi:[1,0]
	v_pk_mul_f32 v[96:97], v[236:237], v[96:97] op_sel_hi:[1,0]
	v_cvt_pk_bf16_f32 v100, v100, v101
	v_cvt_pk_bf16_f32 v101, v96, v97
	global_store_dwordx2 v[98:99], v[100:101], off offset:96 sc1
	ds_read_b64_tr_b16 v[102:103], v128 offset:55296
	ds_read_b64_tr_b16 v[100:101], v128 offset:56448
	ds_read_b128 v[96:99], v104
	ds_read_b128 v[104:107], v104 offset:16
	ds_read_b64_tr_b16 v[192:193], v180 offset:10880
	ds_read_b64_tr_b16 v[190:191], v180 offset:10240
	ds_read_b64_tr_b16 v[194:195], v180 offset:10272
	ds_read_b64_tr_b16 v[196:197], v180 offset:10912
	ds_read_b64_tr_b16 v[198:199], v180 offset:10304
	ds_read_b64_tr_b16 v[200:201], v180 offset:10944
	ds_read_b64_tr_b16 v[202:203], v180 offset:10336
	ds_read_b64_tr_b16 v[204:205], v180 offset:10976
	ds_read_b64_tr_b16 v[206:207], v180 offset:10368
	ds_read_b64_tr_b16 v[208:209], v180 offset:11008
	v_lshlrev_b32_e32 v178, 16, v144
	v_and_b32_e32 v179, 0xffff0000, v144
	v_lshlrev_b32_e32 v144, 16, v145
	v_and_b32_e32 v145, 0xffff0000, v145
	v_pk_mul_f32 v[68:69], v[68:69], v[178:179]
	v_pk_mul_f32 v[70:71], v[70:71], v[144:145]
	v_cvt_pk_bf16_f32 v68, v68, v69
	v_cvt_pk_bf16_f32 v69, v70, v71
	v_lshlrev_b32_e32 v70, 16, v142
	v_and_b32_e32 v71, 0xffff0000, v142
	v_pk_mul_f32 v[56:57], v[56:57], v[70:71]
	s_nop 0
	v_cvt_pk_bf16_f32 v70, v56, v57
	v_lshlrev_b32_e32 v56, 16, v143
	v_and_b32_e32 v57, 0xffff0000, v143
	v_pk_mul_f32 v[56:57], v[58:59], v[56:57]
	s_nop 0
	v_cvt_pk_bf16_f32 v71, v56, v57
	s_nop 1
	v_mfma_f32_16x16x32_bf16 v[52:55], v[68:71], v[52:55], v[76:79]
	v_mfma_f32_16x16x32_bf16 v[48:51], v[68:71], v[48:51], v[80:83]
	v_mfma_f32_16x16x32_bf16 v[56:59], v[68:71], v[60:63], v[84:87]
	v_mfma_f32_16x16x32_bf16 v[60:63], v[68:71], v[64:67], v[88:91]
	v_mfma_f32_16x16x32_bf16 v[64:67], v[68:71], v[72:75], v[92:95]
	v_add_u32_e32 v72, 0x26380, v181
	ds_read_b128 v[68:71], v72
	ds_read_b128 v[72:75], v72 offset:16
	ds_read_b64_tr_b16 v[76:77], v180 offset:15360
	ds_read_b64_tr_b16 v[80:81], v180 offset:15392
	ds_read_b64_tr_b16 v[84:85], v180 offset:15424
	ds_read_b64_tr_b16 v[88:89], v180 offset:15456
	ds_read_b64_tr_b16 v[78:79], v180 offset:16000
	ds_read_b64_tr_b16 v[82:83], v180 offset:16032
	ds_read_b64_tr_b16 v[86:87], v180 offset:16064
	ds_read_b64_tr_b16 v[92:93], v180 offset:15488
	ds_read_b64_tr_b16 v[142:143], v128 offset:64512
	ds_read_b64_tr_b16 v[144:145], v182 offset:28800
	ds_read_b64_tr_b16 v[90:91], v180 offset:16096
	ds_read_b64_tr_b16 v[94:95], v180 offset:16128
	s_waitcnt lgkmcnt(14)
	v_lshlrev_b32_e32 v178, 16, v102
	v_and_b32_e32 v179, 0xffff0000, v102
	v_lshlrev_b32_e32 v102, 16, v103
	v_and_b32_e32 v103, 0xffff0000, v103
	v_pk_mul_f32 v[96:97], v[96:97], v[178:179]
	v_pk_mul_f32 v[98:99], v[98:99], v[102:103]
	v_cvt_pk_bf16_f32 v96, v96, v97
	v_cvt_pk_bf16_f32 v97, v98, v99
	v_lshlrev_b32_e32 v98, 16, v100
	v_and_b32_e32 v99, 0xffff0000, v100
	v_lshlrev_b32_e32 v100, 16, v101
	v_and_b32_e32 v101, 0xffff0000, v101
	v_pk_mul_f32 v[98:99], v[104:105], v[98:99]
	v_pk_mul_f32 v[100:101], v[106:107], v[100:101]
	v_cvt_pk_bf16_f32 v98, v98, v99
	v_cvt_pk_bf16_f32 v99, v100, v101
	s_nop 1
	v_mfma_f32_16x16x32_bf16 v[52:55], v[96:99], v[190:193], v[52:55]
	v_mfma_f32_16x16x32_bf16 v[48:51], v[96:99], v[194:197], v[48:51]
	v_mfma_f32_16x16x32_bf16 v[56:59], v[96:99], v[198:201], v[56:59]
	v_mfma_f32_16x16x32_bf16 v[100:103], v[96:99], v[202:205], v[60:63]
	v_mfma_f32_16x16x32_bf16 v[96:99], v[96:99], v[206:209], v[64:67]
	s_waitcnt lgkmcnt(3)
	s_nop 0
	v_lshlrev_b32_e32 v60, 16, v142
	v_and_b32_e32 v61, 0xffff0000, v142
	v_pk_mul_f32 v[60:61], v[68:69], v[60:61]
	s_add_i32 s16, s16, 1
	v_cvt_pk_bf16_f32 v68, v60, v61
	v_lshlrev_b32_e32 v60, 16, v143
	v_and_b32_e32 v61, 0xffff0000, v143
	v_pk_mul_f32 v[60:61], v[70:71], v[60:61]
	s_add_u32 s76, s76, 0x600
	v_cvt_pk_bf16_f32 v69, v60, v61
	s_waitcnt lgkmcnt(2)
	v_lshlrev_b32_e32 v60, 16, v144
	v_and_b32_e32 v61, 0xffff0000, v144
	v_pk_mul_f32 v[60:61], v[72:73], v[60:61]
	s_addc_u32 s77, s77, 0
	v_cvt_pk_bf16_f32 v70, v60, v61
	v_lshlrev_b32_e32 v60, 16, v145
	v_and_b32_e32 v61, 0xffff0000, v145
	v_pk_mul_f32 v[60:61], v[74:75], v[60:61]
	s_cmp_eq_u32 s17, -1
	v_cvt_pk_bf16_f32 v71, v60, v61
	s_nop 1
	v_mfma_f32_16x16x32_bf16 v[64:67], v[68:71], v[76:79], v[52:55]
	v_mfma_f32_16x16x32_bf16 v[60:63], v[68:71], v[80:83], v[48:51]
	v_mfma_f32_16x16x32_bf16 v[56:59], v[68:71], v[84:87], v[56:59]
	s_waitcnt lgkmcnt(1)
	v_mfma_f32_16x16x32_bf16 v[52:55], v[68:71], v[88:91], v[100:103]
	s_waitcnt lgkmcnt(0)
	v_mfma_f32_16x16x32_bf16 v[48:51], v[68:71], v[92:95], v[96:99]
	v_add_u32_e32 v70, s52, v140
	s_nop 0
	v_cvt_pk_bf16_f32 v68, v64, v65
	v_cvt_pk_bf16_f32 v69, v66, v67
	v_lshl_add_u32 v72, v70, 1, v177
	v_cvt_pk_bf16_f32 v70, v60, v61
	v_cvt_pk_bf16_f32 v71, v62, v63
	ds_write2st64_b64 v72, v[68:69], v[70:71] offset1:9
	v_cvt_pk_bf16_f32 v68, v56, v57
	v_cvt_pk_bf16_f32 v69, v58, v59
	v_cvt_pk_bf16_f32 v70, v52, v53
	v_cvt_pk_bf16_f32 v71, v54, v55
	ds_write2st64_b64 v72, v[68:69], v[70:71] offset0:18 offset1:27
	v_cvt_pk_bf16_f32 v68, v48, v49
	v_cvt_pk_bf16_f32 v69, v50, v51
	ds_write_b64 v72, v[68:69] offset:18432
	s_waitcnt lgkmcnt(0)
	s_barrier
	s_cbranch_scc1 .LBB0_633
	s_mov_b32 s22, s17
	s_branch .LBB0_622
